# v26 with s_sleep 0 instead of s_sleep 1 in the 28 grid-barrier polling loops
# speedup vs baseline: 1.0019x; 1.0019x over previous
; __global__ void __launch_bounds__(512, 2) fwd_kernel(Args a_unused) {
;     ...
;         if (l == 0) grid.sync();
.LBB0_69:
	s_sleep 0
	global_load_dword v1, v161, s[2:3] offset:32 sc1
	s_waitcnt vmcnt(0)
	v_and_b32_e32 v1, 0xffff0000, v1
	v_cmp_ne_u32_e32 vcc, v1, v0
	s_or_b64 s[14:15], vcc, s[14:15]
	s_andn2_b64 exec, exec, s[14:15]
	s_cbranch_execnz .LBB0_69

; __device__ __forceinline__ unsigned xb_ld(unsigned* p)              { return __hip_atomic_load(p, __ATOMIC_RELAXED, __HIP_MEMORY_SCOPE_AGENT); }
; __device__ __forceinline__ void xcd_barrier_complete(unsigned* bar, unsigned x, unsigned& nloc, unsigned& nx) {
;     const unsigned G = gridDim.x * gridDim.y * gridDim.z;
;     unsigned sum, cnt, mine, sp = 0u;
;     for (;;) {
;         sum = 0u; cnt = 0u; mine = 0u;
; #pragma unroll
;         for (unsigned j = 0; j < 16; ++j) { const unsigned c = xb_ld(&bar[XB_XCNT(j)]); sum += c; cnt += (c > 0u) ? 1u : 0u; mine = (j == x) ? c : mine; }
;         if (sum == G) break;
;         __builtin_amdgcn_s_sleep(1);
;         if ((++sp & 255u) == 0u) { if (xb_ld(&bar[XB_TMO])) break; if (sp > XB_SPIN_CAP) { atomicAdd(&bar[XB_TMO], 1u); break; } }
;     }
;     nloc = mine > 0u ? mine : 1u; nx = cnt > 0u ? cnt : 1u;
; }
.LBB0_92:
	v_readlane_b32 s2, v254, 2
	global_load_dword v7, v161, s[76:77] sc1
	s_waitcnt lgkmcnt(0)
	global_load_dword v0, v161, s[78:79] sc1
	global_load_dword v1, v161, s[80:81] sc1
	global_load_dword v2, v161, s[54:55] sc1
	global_load_dword v3, v161, s[56:57] sc1
	global_load_dword v4, v161, s[52:53] sc1
	global_load_dword v5, v161, s[48:49] sc1
	global_load_dword v6, v161, s[50:51] sc1
	v_readlane_b32 s3, v254, 3
	s_mov_b64 s[14:15], -1
	s_waitcnt vmcnt(6)
	v_add_u32_e32 v16, v0, v7
	s_nop 1
	global_load_dword v8, v161, s[2:3] sc1
	v_readlane_b32 s2, v254, 4
	v_readlane_b32 s3, v254, 5
	s_nop 4
	global_load_dword v9, v161, s[2:3] sc1
	global_load_dword v10, v161, s[6:7] sc1
	global_load_dword v11, v161, s[8:9] sc1
	global_load_dword v12, v161, s[10:11] sc1
	global_load_dword v13, v161, s[12:13] sc1
	global_load_dword v14, v161, s[38:39] sc1
	global_load_dword v15, v161, s[4:5] sc1
	s_waitcnt vmcnt(13)
	v_add_u32_e32 v16, v16, v1
	s_waitcnt vmcnt(12)
	v_add_u32_e32 v16, v16, v2
	s_waitcnt vmcnt(11)
	v_add_u32_e32 v16, v16, v3
	s_waitcnt vmcnt(10)
	v_add_u32_e32 v16, v16, v4
	s_waitcnt vmcnt(9)
	v_add_u32_e32 v16, v16, v5
	s_waitcnt vmcnt(8)
	v_add_u32_e32 v16, v16, v6
	s_mov_b64 s[2:3], -1
	s_waitcnt vmcnt(7)
	v_add_u32_e32 v16, v16, v8
	s_waitcnt vmcnt(6)
	v_add_u32_e32 v16, v16, v9
	s_waitcnt vmcnt(5)
	v_add_u32_e32 v16, v16, v10
	s_waitcnt vmcnt(4)
	v_add_u32_e32 v16, v16, v11
	s_waitcnt vmcnt(3)
	v_add_u32_e32 v16, v16, v12
	s_waitcnt vmcnt(2)
	v_add_u32_e32 v16, v16, v13
	s_waitcnt vmcnt(1)
	v_add_u32_e32 v16, v16, v14
	s_waitcnt vmcnt(0)
	v_add_u32_e32 v16, v16, v15
	v_cmp_eq_u32_e32 vcc, s33, v16
	s_cbranch_vccnz .LBB0_91
	s_and_b32 s2, s18, 0xff
	s_cmp_eq_u32 s2, 0
	s_mov_b64 s[2:3], -1
	s_mov_b64 s[16:17], -1
	s_sleep 0
	s_cbranch_scc0 .LBB0_96
	global_load_dword v16, v161, s[90:91] sc1
	s_waitcnt vmcnt(0)
	v_cmp_eq_u32_e32 vcc, 0, v16
	s_cbranch_vccnz .LBB0_98
	s_mov_b64 s[16:17], 0

.LBB0_110:
	s_and_b32 s24, s28, 0xff
	s_mov_b64 s[20:21], -1
	s_cmp_lg_u32 s24, 0
	s_mov_b64 s[26:27], -1
	s_sleep 0
	s_cbranch_scc1 .LBB0_113
	global_load_dword v0, v161, s[90:91] sc1
	s_waitcnt vmcnt(0)
	v_cmp_eq_u32_e32 vcc, 0, v0
	s_cbranch_vccnz .LBB0_115
	s_mov_b64 s[26:27], 0
	s_mov_b64 s[24:25], -1

; __device__ __forceinline__ unsigned xb_ld(unsigned* p)              { return __hip_atomic_load(p, __ATOMIC_RELAXED, __HIP_MEMORY_SCOPE_AGENT); }
; __device__ __forceinline__ void xcd_barrier_complete(unsigned* bar, unsigned x, unsigned& nloc, unsigned& nx) {
;     ...
;     for (;;) {
;         sum = 0u; cnt = 0u; mine = 0u;
; #pragma unroll
;         for (unsigned j = 0; j < 16; ++j) { const unsigned c = xb_ld(&bar[XB_XCNT(j)]); sum += c; cnt += (c > 0u) ? 1u : 0u; mine = (j == x) ? c : mine; }
;         if (sum == G) break;
;         __builtin_amdgcn_s_sleep(1);
;         if ((++sp & 255u) == 0u) { if (xb_ld(&bar[XB_TMO])) break; if (sp > XB_SPIN_CAP) { atomicAdd(&bar[XB_TMO], 1u); break; } }
.LBB0_197:
	v_readlane_b32 s2, v254, 2
	global_load_dword v7, v161, s[76:77] sc1
	s_waitcnt lgkmcnt(0)
	global_load_dword v0, v161, s[78:79] sc1
	global_load_dword v1, v161, s[80:81] sc1
	global_load_dword v2, v161, s[54:55] sc1
	global_load_dword v3, v161, s[56:57] sc1
	global_load_dword v4, v161, s[52:53] sc1
	global_load_dword v5, v161, s[34:35] sc1
	global_load_dword v6, v161, s[36:37] sc1
	v_readlane_b32 s3, v254, 3
	s_mov_b64 s[14:15], -1
	s_waitcnt vmcnt(6)
	v_add_u32_e32 v16, v0, v7
	s_nop 1
	global_load_dword v8, v161, s[2:3] sc1
	v_readlane_b32 s2, v254, 4
	v_readlane_b32 s3, v254, 5
	s_nop 4
	global_load_dword v9, v161, s[2:3] sc1
	global_load_dword v10, v161, s[6:7] sc1
	global_load_dword v11, v161, s[8:9] sc1
	global_load_dword v12, v161, s[10:11] sc1
	global_load_dword v13, v161, s[12:13] sc1
	global_load_dword v14, v161, s[38:39] sc1
	global_load_dword v15, v161, s[4:5] sc1
	s_waitcnt vmcnt(13)
	v_add_u32_e32 v16, v16, v1
	s_waitcnt vmcnt(12)
	v_add_u32_e32 v16, v16, v2
	s_waitcnt vmcnt(11)
	v_add_u32_e32 v16, v16, v3
	s_waitcnt vmcnt(10)
	v_add_u32_e32 v16, v16, v4
	s_waitcnt vmcnt(9)
	v_add_u32_e32 v16, v16, v5
	s_waitcnt vmcnt(8)
	v_add_u32_e32 v16, v16, v6
	s_mov_b64 s[2:3], -1
	s_waitcnt vmcnt(7)
	v_add_u32_e32 v16, v16, v8
	s_waitcnt vmcnt(6)
	v_add_u32_e32 v16, v16, v9
	s_waitcnt vmcnt(5)
	v_add_u32_e32 v16, v16, v10
	s_waitcnt vmcnt(4)
	v_add_u32_e32 v16, v16, v11
	s_waitcnt vmcnt(3)
	v_add_u32_e32 v16, v16, v12
	s_waitcnt vmcnt(2)
	v_add_u32_e32 v16, v16, v13
	s_waitcnt vmcnt(1)
	v_add_u32_e32 v16, v16, v14
	s_waitcnt vmcnt(0)
	v_add_u32_e32 v16, v16, v15
	v_cmp_eq_u32_e32 vcc, s33, v16
	s_cbranch_vccnz .LBB0_196
	s_and_b32 s2, s18, 0xff
	s_cmp_eq_u32 s2, 0
	s_mov_b64 s[2:3], -1
	s_mov_b64 s[16:17], -1
	s_sleep 0
	s_cbranch_scc0 .LBB0_201
	global_load_dword v16, v161, s[90:91] sc1
	s_waitcnt vmcnt(0)
	v_cmp_eq_u32_e32 vcc, 0, v16
	s_cbranch_vccnz .LBB0_203
	s_mov_b64 s[16:17], 0

; __device__ __forceinline__ unsigned xb_ld(unsigned* p)              { return __hip_atomic_load(p, __ATOMIC_RELAXED, __HIP_MEMORY_SCOPE_AGENT); }
; __device__ __forceinline__ void xcd_barrier_complete(unsigned* bar, unsigned x, unsigned& nloc, unsigned& nx) {
;     ...
;     for (;;) {
;         sum = 0u; cnt = 0u; mine = 0u;
; #pragma unroll
;         for (unsigned j = 0; j < 16; ++j) { const unsigned c = xb_ld(&bar[XB_XCNT(j)]); sum += c; cnt += (c > 0u) ? 1u : 0u; mine = (j == x) ? c : mine; }
;         if (sum == G) break;
;         __builtin_amdgcn_s_sleep(1);
;         if ((++sp & 255u) == 0u) { if (xb_ld(&bar[XB_TMO])) break; if (sp > XB_SPIN_CAP) { atomicAdd(&bar[XB_TMO], 1u); break; } }
.LBB0_811:
	v_readlane_b32 s2, v254, 2
	global_load_dword v7, v161, s[76:77] sc1
	s_waitcnt lgkmcnt(0)
	global_load_dword v0, v161, s[78:79] sc1
	global_load_dword v1, v161, s[80:81] sc1
	global_load_dword v2, v161, s[54:55] sc1
	global_load_dword v3, v161, s[56:57] sc1
	global_load_dword v4, v161, s[52:53] sc1
	global_load_dword v5, v161, s[20:21] sc1
	global_load_dword v6, v161, s[24:25] sc1
	v_readlane_b32 s3, v254, 3
	s_mov_b64 s[14:15], -1
	s_waitcnt vmcnt(6)
	v_add_u32_e32 v16, v0, v7
	s_nop 1
	global_load_dword v8, v161, s[2:3] sc1
	v_readlane_b32 s2, v254, 4
	v_readlane_b32 s3, v254, 5
	s_nop 4
	global_load_dword v9, v161, s[2:3] sc1
	global_load_dword v10, v161, s[6:7] sc1
	global_load_dword v11, v161, s[8:9] sc1
	global_load_dword v12, v161, s[10:11] sc1
	global_load_dword v13, v161, s[12:13] sc1
	global_load_dword v14, v161, s[38:39] sc1
	global_load_dword v15, v161, s[4:5] sc1
	s_waitcnt vmcnt(13)
	v_add_u32_e32 v16, v16, v1
	s_waitcnt vmcnt(12)
	v_add_u32_e32 v16, v16, v2
	s_waitcnt vmcnt(11)
	v_add_u32_e32 v16, v16, v3
	s_waitcnt vmcnt(10)
	v_add_u32_e32 v16, v16, v4
	s_waitcnt vmcnt(9)
	v_add_u32_e32 v16, v16, v5
	s_waitcnt vmcnt(8)
	v_add_u32_e32 v16, v16, v6
	s_mov_b64 s[2:3], -1
	s_waitcnt vmcnt(7)
	v_add_u32_e32 v16, v16, v8
	s_waitcnt vmcnt(6)
	v_add_u32_e32 v16, v16, v9
	s_waitcnt vmcnt(5)
	v_add_u32_e32 v16, v16, v10
	s_waitcnt vmcnt(4)
	v_add_u32_e32 v16, v16, v11
	s_waitcnt vmcnt(3)
	v_add_u32_e32 v16, v16, v12
	s_waitcnt vmcnt(2)
	v_add_u32_e32 v16, v16, v13
	s_waitcnt vmcnt(1)
	v_add_u32_e32 v16, v16, v14
	s_waitcnt vmcnt(0)
	v_add_u32_e32 v16, v16, v15
	v_cmp_eq_u32_e32 vcc, s33, v16
	s_cbranch_vccnz .LBB0_810
	s_and_b32 s2, s18, 0xff
	s_cmp_eq_u32 s2, 0
	s_mov_b64 s[2:3], -1
	s_mov_b64 s[16:17], -1
	s_sleep 0
	s_cbranch_scc0 .LBB0_815
	global_load_dword v16, v161, s[90:91] sc1
	s_waitcnt vmcnt(0)
	v_cmp_eq_u32_e32 vcc, 0, v16
	s_cbranch_vccnz .LBB0_817
	s_mov_b64 s[16:17], 0

; __device__ __forceinline__ unsigned xb_ld(unsigned* p)              { return __hip_atomic_load(p, __ATOMIC_RELAXED, __HIP_MEMORY_SCOPE_AGENT); }
; __device__ __forceinline__ void xcd_barrier_complete(unsigned* bar, unsigned x, unsigned& nloc, unsigned& nx) {
;     ...
;     for (;;) {
;         sum = 0u; cnt = 0u; mine = 0u;
; #pragma unroll
;         for (unsigned j = 0; j < 16; ++j) { const unsigned c = xb_ld(&bar[XB_XCNT(j)]); sum += c; cnt += (c > 0u) ? 1u : 0u; mine = (j == x) ? c : mine; }
;         if (sum == G) break;
;         __builtin_amdgcn_s_sleep(1);
;         if ((++sp & 255u) == 0u) { if (xb_ld(&bar[XB_TMO])) break; if (sp > XB_SPIN_CAP) { atomicAdd(&bar[XB_TMO], 1u); break; } }
.LBB0_897:
	v_readlane_b32 s2, v254, 2
	global_load_dword v7, v161, s[76:77] sc1
	s_waitcnt lgkmcnt(0)
	global_load_dword v0, v161, s[78:79] sc1
	global_load_dword v1, v161, s[80:81] sc1
	global_load_dword v2, v161, s[54:55] sc1
	global_load_dword v3, v161, s[56:57] sc1
	global_load_dword v4, v161, s[34:35] sc1
	global_load_dword v5, v161, s[36:37] sc1
	global_load_dword v6, v161, s[40:41] sc1
	v_readlane_b32 s3, v254, 3
	s_mov_b64 s[14:15], -1
	s_waitcnt vmcnt(6)
	v_add_u32_e32 v16, v0, v7
	s_nop 1
	global_load_dword v8, v161, s[2:3] sc1
	v_readlane_b32 s2, v254, 4
	v_readlane_b32 s3, v254, 5
	s_nop 4
	global_load_dword v9, v161, s[2:3] sc1
	global_load_dword v10, v161, s[6:7] sc1
	global_load_dword v11, v161, s[8:9] sc1
	global_load_dword v12, v161, s[10:11] sc1
	global_load_dword v13, v161, s[12:13] sc1
	global_load_dword v14, v161, s[38:39] sc1
	global_load_dword v15, v161, s[4:5] sc1
	s_waitcnt vmcnt(13)
	v_add_u32_e32 v16, v16, v1
	s_waitcnt vmcnt(12)
	v_add_u32_e32 v16, v16, v2
	s_waitcnt vmcnt(11)
	v_add_u32_e32 v16, v16, v3
	s_waitcnt vmcnt(10)
	v_add_u32_e32 v16, v16, v4
	s_waitcnt vmcnt(9)
	v_add_u32_e32 v16, v16, v5
	s_waitcnt vmcnt(8)
	v_add_u32_e32 v16, v16, v6
	s_mov_b64 s[2:3], -1
	s_waitcnt vmcnt(7)
	v_add_u32_e32 v16, v16, v8
	s_waitcnt vmcnt(6)
	v_add_u32_e32 v16, v16, v9
	s_waitcnt vmcnt(5)
	v_add_u32_e32 v16, v16, v10
	s_waitcnt vmcnt(4)
	v_add_u32_e32 v16, v16, v11
	s_waitcnt vmcnt(3)
	v_add_u32_e32 v16, v16, v12
	s_waitcnt vmcnt(2)
	v_add_u32_e32 v16, v16, v13
	s_waitcnt vmcnt(1)
	v_add_u32_e32 v16, v16, v14
	s_waitcnt vmcnt(0)
	v_add_u32_e32 v16, v16, v15
	v_cmp_eq_u32_e32 vcc, s33, v16
	s_cbranch_vccnz .LBB0_896
	s_and_b32 s2, s18, 0xff
	s_cmp_eq_u32 s2, 0
	s_mov_b64 s[2:3], -1
	s_mov_b64 s[16:17], -1
	s_sleep 0
	s_cbranch_scc0 .LBB0_901
	global_load_dword v16, v161, s[90:91] sc1
	s_waitcnt vmcnt(0)
	v_cmp_eq_u32_e32 vcc, 0, v16
	s_cbranch_vccnz .LBB0_903
	s_mov_b64 s[16:17], 0
